# v78 + final RMSNorm rows remapped to the owning row panel (MLP-down L3 -> final norm as a 4-workgroup hand-off) + attention -> O-proj as a point-to-point panel hand-off
# speedup vs baseline: 1.0265x; 1.0004x over previous
; __global__ void __launch_bounds__(NWAVES * 64, 2) fwd_kernel(Args args) {
;     ...
;                 for (int idx = bx; idx < 512; idx += G) {
;                     int tidu = tid; asm volatile("" : "+v"(tidu));
;                     const int xcd = idx & 7, local = (idx >> 3) & 31, i2 = idx >> 8;
;                     const int b = xcd >> 2, kvh = xcd & 3, h = kvh * 2 + i2, qblk = local;
;                     const size_t qoff = ((size_t)(b * SEQ + qblk * 256)) * DM + h * 128;
;                     const size_t koff = (size_t)b * SKV * 512 + kvh * 128;
;                     attn::attn_dense_body((const attn::bf16*)QB + qoff, (const attn::bf16*)KB + koff, (const attn::bf16*)VB + koff, (attn::bf16*)GB + qoff, SKV, (char*)lds, tidu, mnC);
;                 }
.LBB0_1043:
	v_readlane_b32 s0, v254, 2
	s_add_i32 s4, s0, 2
	s_cmp_lt_i32 s4, s81
	s_cbranch_scc0 .LBB0_1109
	s_waitcnt vmcnt(0) lgkmcnt(0)
	s_barrier
	v_cmp_eq_u32_e32 vcc, 0, v215
	s_and_saveexec_b64 s[0:1], vcc
	s_cbranch_execz .Lp2p_w
	s_load_dwordx2 s[2:3], s[94:95], 0xb8
	v_readlane_b32 s101, v255, 12
	s_bfe_u32 s100, s101, 0x10002
	s_lshl_b32 s100, s100, 5
	s_lshr_b32 s6, s101, 3
	s_add_i32 s100, s100, s6
	s_lshl_b32 s100, s100, 5
	s_add_i32 s100, s100, 0x2c00
	s_and_b32 s6, s101, 7
	s_lshl_b32 s6, s6, 3
	s_bfe_u32 s7, s101, 0x30003
	s_add_i32 s6, s6, s7
	s_lshl_b32 s6, s6, 5
	s_add_i32 s6, s6, 0x2c00
	v_mov_b32_e32 v0, s100
	v_mov_b32_e32 v1, 1
	v_mov_b32_e32 v3, s6
	s_waitcnt lgkmcnt(0)
	s_add_u32 s2, s2, 0xe0000
	s_addc_u32 s3, s3, 0
	global_atomic_add v0, v1, s[2:3]
	buffer_inv sc1
	s_mov_b32 s6, 0
.Lp2p_p:
	global_load_dword v2, v3, s[2:3] sc1
	s_waitcnt vmcnt(0)
	v_cmp_le_u32_e32 vcc, 4, v2
	s_cbranch_vccnz .Lp2p_d
	s_sleep 1
	s_add_i32 s6, s6, 1
	s_cmp_lt_u32 s6, 0x100000
	s_cbranch_scc1 .Lp2p_p

.Lp2p_w:
	s_or_b64 exec, exec, s[0:1]
	s_barrier
	s_branch .LBB0_1109
	v_readlane_b32 s0, v254, 3
	v_readlane_b32 s1, v254, 4
	s_andn2_b64 vcc, exec, s[0:1]
	s_cbranch_vccnz .LBB0_1056
	s_barrier
	s_mov_b64 s[0:1], exec
	v_readlane_b32 s2, v255, 6
	v_readlane_b32 s3, v255, 7
	s_and_b64 s[2:3], s[0:1], s[2:3]
	s_mov_b64 exec, s[2:3]
	s_cbranch_execz .LBB0_1055
	v_readlane_b32 s2, v254, 0
	v_readlane_b32 s3, v254, 1
	buffer_wbl2 sc1
	s_waitcnt vmcnt(0)
	s_load_dwordx2 s[2:3], s[2:3], 0x58
	s_mov_b64 s[6:7], exec
	v_mbcnt_lo_u32_b32 v1, s6, 0
	v_mbcnt_hi_u32_b32 v1, s7, v1
	v_cmp_eq_u32_e32 vcc, 0, v1
	s_waitcnt lgkmcnt(0)
	global_load_dword v0, v213, s[2:3] offset:40
	s_and_saveexec_b64 s[12:13], vcc
	s_cbranch_execz .LBB0_1048
	s_bcnt1_i32_b64 s5, s[6:7]
	v_mov_b32_e32 v2, s5
	global_atomic_add v2, v213, v2, s[2:3] offset:32 sc0
